# P4 final epilogue hand-written: all 16 gate loads of the tile in flight (was a 16-step load-wait-multiply-store ladder), on top of v76
# baseline (speedup 1.0000x reference)
.LBB0_531:
	s_andn2_b64 vcc, exec, s[0:1]
	s_mov_b64 s[0:1], -1
	v_lshl_add_u32 v3, v164, 11, v162
	v_lshlrev_b32_e32 v3, 1, v3
	global_load_dwordx4 v[134:137], v3, s[38:39]
	global_load_dwordx4 v[138:141], v3, s[38:39] offset:256
	v_add_u32_e32 v165, 0x10000, v3
	global_load_dwordx4 v[142:145], v165, s[38:39]
	global_load_dwordx4 v[146:149], v165, s[38:39] offset:256
	v_add_u32_e32 v165, 0x20000, v3
	global_load_dwordx4 v[150:153], v165, s[38:39]
	global_load_dwordx4 v[154:157], v165, s[38:39] offset:256
	v_add_u32_e32 v165, 0x30000, v3
	global_load_dwordx4 v[174:177], v165, s[38:39]
	global_load_dwordx4 v[178:181], v165, s[38:39] offset:256
	v_add_u32_e32 v165, 0x80000, v3
	global_load_dwordx4 v[182:185], v165, s[38:39]
	global_load_dwordx4 v[186:189], v165, s[38:39] offset:256
	v_add_u32_e32 v165, 0x90000, v3
	global_load_dwordx4 v[190:193], v165, s[38:39]
	global_load_dwordx4 v[194:197], v165, s[38:39] offset:256
	v_add_u32_e32 v165, 0xa0000, v3
	global_load_dwordx4 v[198:201], v165, s[38:39]
	global_load_dwordx4 v[202:205], v165, s[38:39] offset:256
	v_add_u32_e32 v165, 0xb0000, v3
	global_load_dwordx4 v[206:209], v165, s[38:39]
	global_load_dwordx4 v[210:213], v165, s[38:39] offset:256
	s_waitcnt vmcnt(14)
	v_lshlrev_b32_e32 v4, 16, v134
	v_and_b32_e32 v5, 0xffff0000, v134
	v_pk_mul_f32 v[130:131], v[130:131], v[4:5]
	v_lshlrev_b32_e32 v134, 16, v135
	v_and_b32_e32 v135, 0xffff0000, v135
	v_pk_mul_f32 v[132:133], v[132:133], v[134:135]
	v_lshlrev_b32_e32 v4, 16, v136
	v_and_b32_e32 v5, 0xffff0000, v136
	v_pk_mul_f32 v[126:127], v[126:127], v[4:5]
	v_lshlrev_b32_e32 v136, 16, v137
	v_and_b32_e32 v137, 0xffff0000, v137
	v_pk_mul_f32 v[128:129], v[128:129], v[136:137]
	v_cvt_pk_bf16_f32 v134, v130, v131
	v_cvt_pk_bf16_f32 v135, v132, v133
	v_cvt_pk_bf16_f32 v136, v126, v127
	v_cvt_pk_bf16_f32 v137, v128, v129
	v_lshlrev_b32_e32 v4, 16, v138
	v_and_b32_e32 v5, 0xffff0000, v138
	v_pk_mul_f32 v[122:123], v[122:123], v[4:5]
	v_lshlrev_b32_e32 v138, 16, v139
	v_and_b32_e32 v139, 0xffff0000, v139
	v_pk_mul_f32 v[124:125], v[124:125], v[138:139]
	v_lshlrev_b32_e32 v4, 16, v140
	v_and_b32_e32 v5, 0xffff0000, v140
	v_pk_mul_f32 v[118:119], v[118:119], v[4:5]
	v_lshlrev_b32_e32 v140, 16, v141
	v_and_b32_e32 v141, 0xffff0000, v141
	v_pk_mul_f32 v[120:121], v[120:121], v[140:141]
	v_cvt_pk_bf16_f32 v138, v122, v123
	v_cvt_pk_bf16_f32 v139, v124, v125
	v_cvt_pk_bf16_f32 v140, v118, v119
	v_cvt_pk_bf16_f32 v141, v120, v121
	global_store_dwordx4 v3, v[134:137], s[12:13]
	global_store_dwordx4 v3, v[138:141], s[12:13] offset:256
	s_waitcnt vmcnt(14)
	v_lshlrev_b32_e32 v4, 16, v142
	v_and_b32_e32 v5, 0xffff0000, v142
	v_pk_mul_f32 v[114:115], v[114:115], v[4:5]
	v_lshlrev_b32_e32 v142, 16, v143
	v_and_b32_e32 v143, 0xffff0000, v143
	v_pk_mul_f32 v[116:117], v[116:117], v[142:143]
	v_lshlrev_b32_e32 v4, 16, v144
	v_and_b32_e32 v5, 0xffff0000, v144
	v_pk_mul_f32 v[110:111], v[110:111], v[4:5]
	v_lshlrev_b32_e32 v144, 16, v145
	v_and_b32_e32 v145, 0xffff0000, v145
	v_pk_mul_f32 v[112:113], v[112:113], v[144:145]
	v_cvt_pk_bf16_f32 v142, v114, v115
	v_cvt_pk_bf16_f32 v143, v116, v117
	v_cvt_pk_bf16_f32 v144, v110, v111
	v_cvt_pk_bf16_f32 v145, v112, v113
	v_lshlrev_b32_e32 v4, 16, v146
	v_and_b32_e32 v5, 0xffff0000, v146
	v_pk_mul_f32 v[106:107], v[106:107], v[4:5]
	v_lshlrev_b32_e32 v146, 16, v147
	v_and_b32_e32 v147, 0xffff0000, v147
	v_pk_mul_f32 v[108:109], v[108:109], v[146:147]
	v_lshlrev_b32_e32 v4, 16, v148
	v_and_b32_e32 v5, 0xffff0000, v148
	v_pk_mul_f32 v[102:103], v[102:103], v[4:5]
	v_lshlrev_b32_e32 v148, 16, v149
	v_and_b32_e32 v149, 0xffff0000, v149
	v_pk_mul_f32 v[104:105], v[104:105], v[148:149]
	v_cvt_pk_bf16_f32 v146, v106, v107
	v_cvt_pk_bf16_f32 v147, v108, v109
	v_cvt_pk_bf16_f32 v148, v102, v103
	v_cvt_pk_bf16_f32 v149, v104, v105
	v_add_u32_e32 v165, 0x10000, v3
	global_store_dwordx4 v165, v[142:145], s[12:13]
	global_store_dwordx4 v165, v[146:149], s[12:13] offset:256
	s_waitcnt vmcnt(14)
	v_lshlrev_b32_e32 v4, 16, v150
	v_and_b32_e32 v5, 0xffff0000, v150
	v_pk_mul_f32 v[98:99], v[98:99], v[4:5]
	v_lshlrev_b32_e32 v150, 16, v151
	v_and_b32_e32 v151, 0xffff0000, v151
	v_pk_mul_f32 v[100:101], v[100:101], v[150:151]
	v_lshlrev_b32_e32 v4, 16, v152
	v_and_b32_e32 v5, 0xffff0000, v152
	v_pk_mul_f32 v[94:95], v[94:95], v[4:5]
	v_lshlrev_b32_e32 v152, 16, v153
	v_and_b32_e32 v153, 0xffff0000, v153
	v_pk_mul_f32 v[96:97], v[96:97], v[152:153]
	v_cvt_pk_bf16_f32 v150, v98, v99
	v_cvt_pk_bf16_f32 v151, v100, v101
	v_cvt_pk_bf16_f32 v152, v94, v95
	v_cvt_pk_bf16_f32 v153, v96, v97
	v_lshlrev_b32_e32 v4, 16, v154
	v_and_b32_e32 v5, 0xffff0000, v154
	v_pk_mul_f32 v[90:91], v[90:91], v[4:5]
	v_lshlrev_b32_e32 v154, 16, v155
	v_and_b32_e32 v155, 0xffff0000, v155
	v_pk_mul_f32 v[92:93], v[92:93], v[154:155]
	v_lshlrev_b32_e32 v4, 16, v156
	v_and_b32_e32 v5, 0xffff0000, v156
	v_pk_mul_f32 v[86:87], v[86:87], v[4:5]
	v_lshlrev_b32_e32 v156, 16, v157
	v_and_b32_e32 v157, 0xffff0000, v157
	v_pk_mul_f32 v[88:89], v[88:89], v[156:157]
	v_cvt_pk_bf16_f32 v154, v90, v91
	v_cvt_pk_bf16_f32 v155, v92, v93
	v_cvt_pk_bf16_f32 v156, v86, v87
	v_cvt_pk_bf16_f32 v157, v88, v89
	v_add_u32_e32 v165, 0x20000, v3
	global_store_dwordx4 v165, v[150:153], s[12:13]
	global_store_dwordx4 v165, v[154:157], s[12:13] offset:256
	s_waitcnt vmcnt(14)
	v_lshlrev_b32_e32 v4, 16, v174
	v_and_b32_e32 v5, 0xffff0000, v174
	v_pk_mul_f32 v[82:83], v[82:83], v[4:5]
	v_lshlrev_b32_e32 v174, 16, v175
	v_and_b32_e32 v175, 0xffff0000, v175
	v_pk_mul_f32 v[84:85], v[84:85], v[174:175]
	v_lshlrev_b32_e32 v4, 16, v176
	v_and_b32_e32 v5, 0xffff0000, v176
	v_pk_mul_f32 v[78:79], v[78:79], v[4:5]
	v_lshlrev_b32_e32 v176, 16, v177
	v_and_b32_e32 v177, 0xffff0000, v177
	v_pk_mul_f32 v[80:81], v[80:81], v[176:177]
	v_cvt_pk_bf16_f32 v174, v82, v83
	v_cvt_pk_bf16_f32 v175, v84, v85
	v_cvt_pk_bf16_f32 v176, v78, v79
	v_cvt_pk_bf16_f32 v177, v80, v81
	v_lshlrev_b32_e32 v4, 16, v178
	v_and_b32_e32 v5, 0xffff0000, v178
	v_pk_mul_f32 v[74:75], v[74:75], v[4:5]
	v_lshlrev_b32_e32 v178, 16, v179
	v_and_b32_e32 v179, 0xffff0000, v179
	v_pk_mul_f32 v[76:77], v[76:77], v[178:179]
	v_lshlrev_b32_e32 v4, 16, v180
	v_and_b32_e32 v5, 0xffff0000, v180
	v_pk_mul_f32 v[70:71], v[70:71], v[4:5]
	v_lshlrev_b32_e32 v180, 16, v181
	v_and_b32_e32 v181, 0xffff0000, v181
	v_pk_mul_f32 v[72:73], v[72:73], v[180:181]
	v_cvt_pk_bf16_f32 v178, v74, v75
	v_cvt_pk_bf16_f32 v179, v76, v77
	v_cvt_pk_bf16_f32 v180, v70, v71
	v_cvt_pk_bf16_f32 v181, v72, v73
	v_add_u32_e32 v165, 0x30000, v3
	global_store_dwordx4 v165, v[174:177], s[12:13]
	global_store_dwordx4 v165, v[178:181], s[12:13] offset:256
	s_waitcnt vmcnt(14)
	v_lshlrev_b32_e32 v4, 16, v182
	v_and_b32_e32 v5, 0xffff0000, v182
	v_pk_mul_f32 v[66:67], v[66:67], v[4:5]
	v_lshlrev_b32_e32 v182, 16, v183
	v_and_b32_e32 v183, 0xffff0000, v183
	v_pk_mul_f32 v[68:69], v[68:69], v[182:183]
	v_lshlrev_b32_e32 v4, 16, v184
	v_and_b32_e32 v5, 0xffff0000, v184
	v_pk_mul_f32 v[62:63], v[62:63], v[4:5]
	v_lshlrev_b32_e32 v184, 16, v185
	v_and_b32_e32 v185, 0xffff0000, v185
	v_pk_mul_f32 v[64:65], v[64:65], v[184:185]
	v_cvt_pk_bf16_f32 v182, v66, v67
	v_cvt_pk_bf16_f32 v183, v68, v69
	v_cvt_pk_bf16_f32 v184, v62, v63
	v_cvt_pk_bf16_f32 v185, v64, v65
	v_lshlrev_b32_e32 v4, 16, v186
	v_and_b32_e32 v5, 0xffff0000, v186
	v_pk_mul_f32 v[58:59], v[58:59], v[4:5]
	v_lshlrev_b32_e32 v186, 16, v187
	v_and_b32_e32 v187, 0xffff0000, v187
	v_pk_mul_f32 v[60:61], v[60:61], v[186:187]
	v_lshlrev_b32_e32 v4, 16, v188
	v_and_b32_e32 v5, 0xffff0000, v188
	v_pk_mul_f32 v[54:55], v[54:55], v[4:5]
	v_lshlrev_b32_e32 v188, 16, v189
	v_and_b32_e32 v189, 0xffff0000, v189
	v_pk_mul_f32 v[56:57], v[56:57], v[188:189]
	v_cvt_pk_bf16_f32 v186, v58, v59
	v_cvt_pk_bf16_f32 v187, v60, v61
	v_cvt_pk_bf16_f32 v188, v54, v55
	v_cvt_pk_bf16_f32 v189, v56, v57
	v_add_u32_e32 v165, 0x80000, v3
	global_store_dwordx4 v165, v[182:185], s[12:13]
	global_store_dwordx4 v165, v[186:189], s[12:13] offset:256
	s_waitcnt vmcnt(14)
	v_lshlrev_b32_e32 v4, 16, v190
	v_and_b32_e32 v5, 0xffff0000, v190
	v_pk_mul_f32 v[50:51], v[50:51], v[4:5]
	v_lshlrev_b32_e32 v190, 16, v191
	v_and_b32_e32 v191, 0xffff0000, v191
	v_pk_mul_f32 v[52:53], v[52:53], v[190:191]
	v_lshlrev_b32_e32 v4, 16, v192
	v_and_b32_e32 v5, 0xffff0000, v192
	v_pk_mul_f32 v[46:47], v[46:47], v[4:5]
	v_lshlrev_b32_e32 v192, 16, v193
	v_and_b32_e32 v193, 0xffff0000, v193
	v_pk_mul_f32 v[48:49], v[48:49], v[192:193]
	v_cvt_pk_bf16_f32 v190, v50, v51
	v_cvt_pk_bf16_f32 v191, v52, v53
	v_cvt_pk_bf16_f32 v192, v46, v47
	v_cvt_pk_bf16_f32 v193, v48, v49
	v_lshlrev_b32_e32 v4, 16, v194
	v_and_b32_e32 v5, 0xffff0000, v194
	v_pk_mul_f32 v[42:43], v[42:43], v[4:5]
	v_lshlrev_b32_e32 v194, 16, v195
	v_and_b32_e32 v195, 0xffff0000, v195
	v_pk_mul_f32 v[44:45], v[44:45], v[194:195]
	v_lshlrev_b32_e32 v4, 16, v196
	v_and_b32_e32 v5, 0xffff0000, v196
	v_pk_mul_f32 v[38:39], v[38:39], v[4:5]
	v_lshlrev_b32_e32 v196, 16, v197
	v_and_b32_e32 v197, 0xffff0000, v197
	v_pk_mul_f32 v[40:41], v[40:41], v[196:197]
	v_cvt_pk_bf16_f32 v194, v42, v43
	v_cvt_pk_bf16_f32 v195, v44, v45
	v_cvt_pk_bf16_f32 v196, v38, v39
	v_cvt_pk_bf16_f32 v197, v40, v41
	v_add_u32_e32 v165, 0x90000, v3
	global_store_dwordx4 v165, v[190:193], s[12:13]
	global_store_dwordx4 v165, v[194:197], s[12:13] offset:256
	s_waitcnt vmcnt(14)
	v_lshlrev_b32_e32 v4, 16, v198
	v_and_b32_e32 v5, 0xffff0000, v198
	v_pk_mul_f32 v[34:35], v[34:35], v[4:5]
	v_lshlrev_b32_e32 v198, 16, v199
	v_and_b32_e32 v199, 0xffff0000, v199
	v_pk_mul_f32 v[36:37], v[36:37], v[198:199]
	v_lshlrev_b32_e32 v4, 16, v200
	v_and_b32_e32 v5, 0xffff0000, v200
	v_pk_mul_f32 v[30:31], v[30:31], v[4:5]
	v_lshlrev_b32_e32 v200, 16, v201
	v_and_b32_e32 v201, 0xffff0000, v201
	v_pk_mul_f32 v[32:33], v[32:33], v[200:201]
	v_cvt_pk_bf16_f32 v198, v34, v35
	v_cvt_pk_bf16_f32 v199, v36, v37
	v_cvt_pk_bf16_f32 v200, v30, v31
	v_cvt_pk_bf16_f32 v201, v32, v33
	v_lshlrev_b32_e32 v4, 16, v202
	v_and_b32_e32 v5, 0xffff0000, v202
	v_pk_mul_f32 v[26:27], v[26:27], v[4:5]
	v_lshlrev_b32_e32 v202, 16, v203
	v_and_b32_e32 v203, 0xffff0000, v203
	v_pk_mul_f32 v[28:29], v[28:29], v[202:203]
	v_lshlrev_b32_e32 v4, 16, v204
	v_and_b32_e32 v5, 0xffff0000, v204
	v_pk_mul_f32 v[22:23], v[22:23], v[4:5]
	v_lshlrev_b32_e32 v204, 16, v205
	v_and_b32_e32 v205, 0xffff0000, v205
	v_pk_mul_f32 v[24:25], v[24:25], v[204:205]
	v_cvt_pk_bf16_f32 v202, v26, v27
	v_cvt_pk_bf16_f32 v203, v28, v29
	v_cvt_pk_bf16_f32 v204, v22, v23
	v_cvt_pk_bf16_f32 v205, v24, v25
	v_add_u32_e32 v165, 0xa0000, v3
	global_store_dwordx4 v165, v[198:201], s[12:13]
	global_store_dwordx4 v165, v[202:205], s[12:13] offset:256
	s_waitcnt vmcnt(14)
	v_lshlrev_b32_e32 v4, 16, v206
	v_and_b32_e32 v5, 0xffff0000, v206
	v_pk_mul_f32 v[18:19], v[18:19], v[4:5]
	v_lshlrev_b32_e32 v206, 16, v207
	v_and_b32_e32 v207, 0xffff0000, v207
	v_pk_mul_f32 v[20:21], v[20:21], v[206:207]
	v_lshlrev_b32_e32 v4, 16, v208
	v_and_b32_e32 v5, 0xffff0000, v208
	v_pk_mul_f32 v[14:15], v[14:15], v[4:5]
	v_lshlrev_b32_e32 v208, 16, v209
	v_and_b32_e32 v209, 0xffff0000, v209
	v_pk_mul_f32 v[16:17], v[16:17], v[208:209]
	v_cvt_pk_bf16_f32 v206, v18, v19
	v_cvt_pk_bf16_f32 v207, v20, v21
	v_cvt_pk_bf16_f32 v208, v14, v15
	v_cvt_pk_bf16_f32 v209, v16, v17
	v_lshlrev_b32_e32 v4, 16, v210
	v_and_b32_e32 v5, 0xffff0000, v210
	v_pk_mul_f32 v[10:11], v[10:11], v[4:5]
	v_lshlrev_b32_e32 v210, 16, v211
	v_and_b32_e32 v211, 0xffff0000, v211
	v_pk_mul_f32 v[12:13], v[12:13], v[210:211]
	v_lshlrev_b32_e32 v4, 16, v212
	v_and_b32_e32 v5, 0xffff0000, v212
	v_pk_mul_f32 v[6:7], v[6:7], v[4:5]
	v_lshlrev_b32_e32 v212, 16, v213
	v_and_b32_e32 v213, 0xffff0000, v213
	v_pk_mul_f32 v[8:9], v[8:9], v[212:213]
	v_cvt_pk_bf16_f32 v210, v10, v11
	v_cvt_pk_bf16_f32 v211, v12, v13
	v_cvt_pk_bf16_f32 v212, v6, v7
	v_cvt_pk_bf16_f32 v213, v8, v9
	v_add_u32_e32 v165, 0xb0000, v3
	global_store_dwordx4 v165, v[206:209], s[12:13]
	global_store_dwordx4 v165, v[210:213], s[12:13] offset:256
	s_cbranch_vccnz .LBB0_515
	s_andn2_b64 vcc, exec, s[8:9]
	s_cbranch_vccnz .LBB0_514
	s_barrier
	s_branch .LBB0_514
